# HGRN phase C dir-1: prefetch stash loads at chunk head, hoist loop-invariant gain loads, DPP butterfly instead of bpermute
# baseline (speedup 1.0000x reference)
.LBB0_720:
	s_xor_b64 s[78:79], s[76:77], -1
	s_and_b64 s[22:23], s[76:77], exec
	s_cselect_b32 s22, 0, 0xe0
	v_add_u32_e32 v2, s22, v135
	s_mov_b32 s23, 0xfa22000
	v_ashrrev_i32_e32 v3, 31, v2
	s_cselect_b32 s23, s23, 0x12222000
	v_lshlrev_b64 v[2:3], 9, v[2:3]
	s_add_u32 s80, s34, s23
	v_or_b32_e32 v2, v2, v112
	s_addc_u32 s81, s35, 0
	v_lshlrev_b64 v[36:37], 1, v[2:3]
	v_lshl_add_u64 v[38:39], s[42:43], 0, v[36:37]
	v_lshl_add_u64 v[40:41], s[80:81], 0, v[36:37]
	v_lshl_add_u64 v[36:37], s[40:41], 0, v[36:37]
	global_load_dwordx4 v[56:59], v[38:39], off
	global_load_dwordx4 v[60:63], v[40:41], off
	global_load_dwordx4 v[68:71], v[36:37], off
	global_load_dwordx4 v[246:249], v[110:111], off offset:16
	global_load_dwordx4 v[250:253], v[110:111], off
	v_cndmask_b32_e64 v0, 0, 1, s[78:79]
	v_cmp_ne_u32_e64 s[22:23], 1, v0
	s_andn2_b64 vcc, exec, s[78:79]
	s_cbranch_vccnz .LBB0_722
	v_lshl_add_u64 v[2:3], v[2:3], 1, s[44:45]
	global_load_dwordx4 v[52:55], v[2:3], off
	s_andn2_b64 s[28:29], s[72:73], exec
	s_and_b64 s[82:83], s[20:21], exec
	s_or_b64 s[82:83], s[28:29], s[82:83]
	s_andn2_b64 s[28:29], s[56:57], exec
	s_and_b64 s[84:85], s[18:19], exec
	s_or_b64 s[84:85], s[28:29], s[84:85]
	s_andn2_b64 s[28:29], s[54:55], exec
	s_and_b64 s[86:87], s[16:17], exec
	s_or_b64 s[86:87], s[28:29], s[86:87]
	s_andn2_b64 s[28:29], s[52:53], exec
	s_and_b64 s[88:89], s[14:15], exec
	s_mov_b32 s24, 0
	s_or_b64 s[88:89], s[28:29], s[88:89]
	s_branch .LBB0_723

.LBB0_728:
	s_and_b64 vcc, exec, s[78:79]
	s_cbranch_vccz .Lhc_nostash
	s_sub_i32 s90, 7, s27
	s_lshl_b32 s90, s90, 14
	v_lshlrev_b32_e32 v238, 2, v164
	v_or_b32_e32 v238, s90, v238
	v_add_u32_e32 v242, 0x2000, v238
	global_load_dwordx4 v[238:241], v238, s[50:51]
	global_load_dwordx4 v[242:245], v242, s[50:51]

.LBB0_746:
	s_or_b64 exec, exec, s[90:91]
	s_waitcnt lgkmcnt(0)
	s_barrier
	ds_read_b128 v[56:59], v116 offset:60672
	ds_read_b128 v[68:71], v131
	s_sub_i32 s90, 7, s27
	s_and_b64 s[28:29], s[76:77], exec
	s_waitcnt lgkmcnt(0)
	v_mfma_f32_16x16x32_bf16 v[64:67], v[68:71], v[56:59], v[64:67]
	ds_read_b128 v[68:71], v131 offset:1280
	s_cselect_b32 s92, s27, s90
	v_lshl_or_b32 v0, s92, 12, v164
	v_lshl_add_u64 v[2:3], v[0:1], 2, s[50:51]
	s_mov_b64 s[90:91], -1
	s_and_b64 vcc, exec, s[78:79]
	s_waitcnt lgkmcnt(0)
	v_mfma_f32_16x16x32_bf16 v[60:63], v[68:71], v[56:59], v[60:63]
	s_cbranch_vccz .LBB0_748
	s_mov_b64 s[90:91], 0
	s_waitcnt vmcnt(0)
	s_nop 7
	v_add_f32_e32 v0, v64, v238
	v_add_f32_e32 v69, v65, v239
	ds_write2_b32 v122, v0, v69 offset1:132
	v_add_f32_e32 v68, v60, v242
	v_add_f32_e32 v0, v61, v243
	v_add_u32_e32 v69, 0x2000, v122
	ds_write2_b32 v69, v68, v0 offset0:64 offset1:196
	v_add_f32_e32 v0, v66, v240
	v_add_f32_e32 v69, v67, v241
	v_add_u32_e32 v70, 0x400, v122
	v_add_f32_e32 v68, v62, v244
	ds_write2_b32 v70, v0, v69 offset0:8 offset1:140
	v_add_f32_e32 v0, v63, v245
	v_add_u32_e32 v69, 0x2400, v122
	ds_write2_b32 v69, v68, v0 offset0:72 offset1:204

.LBB0_750:
	v_add_u32_e32 v0, 0x1ec00, v105
	s_nop 3
	ds_read_b128 v[206:209], v0
	ds_read_b128 v[210:213], v0 offset:64
	ds_read_b128 v[214:217], v0 offset:128
	ds_read_b128 v[218:221], v0 offset:192
	ds_read_b128 v[222:225], v0 offset:256
	ds_read_b128 v[226:229], v0 offset:320
	ds_read_b128 v[230:233], v0 offset:384
	ds_read_b128 v[234:237], v0 offset:448
	ds_read_b128 v[238:241], v120 offset:50176
	ds_read_b128 v[242:245], v119 offset:50176
	ds_read_b128 v[60:63], v118 offset:50176
	ds_read_b128 v[64:67], v123 offset:50176
	ds_read_b128 v[68:71], v124 offset:50176
	ds_read_b128 v[168:171], v125 offset:50176
	ds_read_b128 v[172:175], v126 offset:50176
	ds_read_b128 v[176:179], v127 offset:50176
	s_and_b64 vcc, exec, s[22:23]
	s_waitcnt lgkmcnt(7)
	v_pk_mul_f32 v[2:3], v[4:5], v[206:207]
	v_pk_mul_f32 v[4:5], v[6:7], v[208:209]
	v_pk_mul_f32 v[16:17], v[16:17], v[210:211]
	v_pk_mul_f32 v[18:19], v[18:19], v[212:213]
	v_pk_mul_f32 v[8:9], v[8:9], v[214:215]
	v_pk_mul_f32 v[10:11], v[10:11], v[216:217]
	v_pk_mul_f32 v[12:13], v[12:13], v[218:219]
	v_pk_mul_f32 v[14:15], v[14:15], v[220:221]
	v_pk_mul_f32 v[20:21], v[20:21], v[222:223]
	v_pk_mul_f32 v[22:23], v[22:23], v[224:225]
	v_pk_mul_f32 v[28:29], v[28:29], v[226:227]
	v_pk_mul_f32 v[30:31], v[30:31], v[228:229]
	v_pk_mul_f32 v[24:25], v[24:25], v[230:231]
	v_pk_mul_f32 v[26:27], v[26:27], v[232:233]
	v_pk_mul_f32 v[32:33], v[32:33], v[234:235]
	v_pk_mul_f32 v[34:35], v[34:35], v[236:237]
	v_mfma_f32_16x16x32_bf16 v[4:7], v[238:241], v[56:59], v[2:5]
	s_waitcnt lgkmcnt(6)
	v_mfma_f32_16x16x32_bf16 v[16:19], v[242:245], v[56:59], v[16:19]
	s_waitcnt lgkmcnt(5)
	v_mfma_f32_16x16x32_bf16 v[8:11], v[60:63], v[56:59], v[8:11]
	s_waitcnt lgkmcnt(4)
	v_mfma_f32_16x16x32_bf16 v[12:15], v[64:67], v[56:59], v[12:15]
	s_waitcnt lgkmcnt(3)
	v_mfma_f32_16x16x32_bf16 v[20:23], v[68:71], v[56:59], v[20:23]
	s_waitcnt lgkmcnt(2)
	v_mfma_f32_16x16x32_bf16 v[28:31], v[168:171], v[56:59], v[28:31]
	s_waitcnt lgkmcnt(1)
	v_mfma_f32_16x16x32_bf16 v[24:27], v[172:175], v[56:59], v[24:27]
	s_waitcnt lgkmcnt(0)
	s_barrier
	v_mfma_f32_16x16x32_bf16 v[32:35], v[176:179], v[56:59], v[32:35]
	s_cbranch_vccnz .LBB0_724
	ds_read_b128 v[64:67], v132
	ds_read_b128 v[56:59], v132 offset:16
	s_mov_b32 s28, 0x800000
	v_lshl_add_u32 v2, s92, 5, v135
	v_ashrrev_i32_e32 v3, 31, v2
	v_lshlrev_b64 v[2:3], 10, v[2:3]
	s_waitcnt lgkmcnt(0)
	v_pk_mul_f32 v[62:63], v[56:57], v[56:57]
	v_pk_mul_f32 v[60:61], v[58:59], v[58:59]
	v_pk_fma_f32 v[62:63], v[64:65], v[64:65], v[62:63]
	v_pk_fma_f32 v[60:61], v[66:67], v[66:67], v[60:61]
	v_add_f32_e32 v0, v62, v63
	v_add_f32_e32 v0, v60, v0
	v_add_f32_e32 v0, v61, v0
	v_lshl_add_u64 v[2:3], v[108:109], 0, v[2:3]
	s_nop 1
	v_add_f32_dpp v0, v0, v0 quad_perm:[1,0,3,2] row_mask:0xf bank_mask:0xf
	s_nop 1
	v_add_f32_dpp v0, v0, v0 quad_perm:[2,3,0,1] row_mask:0xf bank_mask:0xf
	s_nop 1
	v_add_f32_dpp v0, v0, v0 row_half_mirror row_mask:0xf bank_mask:0xf
	s_nop 1
	v_add_f32_dpp v0, v0, v0 row_mirror row_mask:0xf bank_mask:0xf
	v_fmamk_f32 v0, v0, 0x3c000000, v133
	v_cmp_gt_f32_e32 vcc, s28, v0
	v_mul_f32_e32 v60, 0x4b800000, v0
	s_nop 0
	v_cndmask_b32_e32 v0, v0, v60, vcc
	v_rsq_f32_e32 v0, v0
	s_nop 0
	v_mul_f32_e32 v60, 0x45800000, v0
	v_cndmask_b32_e32 v0, v0, v60, vcc
	v_pk_mul_f32 v[64:65], v[64:65], v[0:1] op_sel_hi:[1,0]
	v_pk_mul_f32 v[66:67], v[66:67], v[0:1] op_sel_hi:[1,0]
	v_pk_mul_f32 v[64:65], v[250:251], v[64:65]
	v_lshlrev_b32_e32 v68, 16, v52
	v_and_b32_e32 v69, 0xffff0000, v52
	v_pk_mul_f32 v[66:67], v[252:253], v[66:67]
	v_lshlrev_b32_e32 v52, 16, v53
	v_and_b32_e32 v53, 0xffff0000, v53
	v_pk_mul_f32 v[66:67], v[66:67], v[52:53]
	v_pk_mul_f32 v[52:53], v[56:57], v[0:1] op_sel_hi:[1,0]
	v_lshlrev_b32_e32 v56, 16, v54
	v_pk_mul_f32 v[52:53], v[246:247], v[52:53]
	v_and_b32_e32 v57, 0xffff0000, v54
	v_pk_mul_f32 v[56:57], v[52:53], v[56:57]
	v_pk_mul_f32 v[52:53], v[58:59], v[0:1] op_sel_hi:[1,0]
	v_lshlrev_b32_e32 v54, 16, v55
	v_pk_mul_f32 v[52:53], v[248:249], v[52:53]
	v_and_b32_e32 v55, 0xffff0000, v55
	v_pk_mul_f32 v[64:65], v[64:65], v[68:69]
	v_pk_mul_f32 v[58:59], v[52:53], v[54:55]
	v_cvt_pk_bf16_f32 v52, v64, v65
	v_cvt_pk_bf16_f32 v53, v66, v67
	v_cvt_pk_bf16_f32 v54, v56, v57
	v_cvt_pk_bf16_f32 v55, v58, v59
	global_store_dwordx4 v[2:3], v[52:55], off
	s_branch .LBB0_724
